# GQA epilogue: hoist 30 gate loads above last-tile PV, H blocks processed first
# baseline (speedup 1.0000x reference)
.LBB0_300:
	v_add_f32_e32 v82, v82, v83
	v_fmac_f32_e32 v82, v114, v98
	v_add3_u32 v162, v188, v190, v196
	s_add_u32 s36, s8, 0x14000
	s_addc_u32 s37, s9, 0
	global_load_ushort v100, v162, s[36:37] offset:3200
	global_load_ushort v101, v162, s[36:37] offset:3264
	s_add_u32 s36, s36, 0x1400
	s_addc_u32 s37, s37, 0
	global_load_ushort v102, v162, s[36:37] offset:3072
	global_load_ushort v103, v162, s[36:37] offset:3136
	global_load_ushort v104, v162, s[36:37] offset:3200
	global_load_ushort v105, v162, s[36:37] offset:3264
	s_add_u32 s36, s36, 0x1400
	s_addc_u32 s37, s37, 0
	global_load_ushort v106, v162, s[36:37] offset:3072
	global_load_ushort v107, v162, s[36:37] offset:3136
	global_load_ushort v108, v162, s[36:37] offset:3200
	global_load_ushort v109, v162, s[36:37] offset:3264
	s_add_u32 s36, s36, 0x1400
	s_addc_u32 s37, s37, 0
	global_load_ushort v110, v162, s[36:37] offset:3072
	global_load_ushort v111, v162, s[36:37] offset:3136
	global_load_ushort v112, v162, s[36:37] offset:3200
	global_load_ushort v113, v162, s[36:37] offset:3264
	s_add_u32 s36, s36, 0x6400
	s_addc_u32 s37, s37, 0
	global_load_ushort v114, v162, s[36:37] offset:3072
	global_load_ushort v115, v162, s[36:37] offset:3136
	global_load_ushort v116, v162, s[36:37] offset:3200
	global_load_ushort v117, v162, s[36:37] offset:3264
	s_add_u32 s36, s36, 0x1400
	s_addc_u32 s37, s37, 0
	global_load_ushort v118, v162, s[36:37] offset:3072
	global_load_ushort v119, v162, s[36:37] offset:3136
	global_load_ushort v120, v162, s[36:37] offset:3200
	global_load_ushort v121, v162, s[36:37] offset:3264
	s_add_u32 s36, s36, 0x1400
	s_addc_u32 s37, s37, 0
	global_load_ushort v122, v162, s[36:37] offset:3072
	global_load_ushort v123, v162, s[36:37] offset:3136
	global_load_ushort v124, v162, s[36:37] offset:3200
	global_load_ushort v125, v162, s[36:37] offset:3264
	s_add_u32 s36, s36, 0x1400
	s_addc_u32 s37, s37, 0
	global_load_ushort v126, v162, s[36:37] offset:3072
	global_load_ushort v127, v162, s[36:37] offset:3136
	global_load_ushort v128, v162, s[36:37] offset:3200
	global_load_ushort v129, v162, s[36:37] offset:3264
	s_nop 0
	s_nop 0
	s_nop 0
	s_nop 0
	s_nop 0
	s_nop 0
	s_nop 0
	s_nop 0
	s_nop 0
	s_nop 0
	s_waitcnt vmcnt(30)
	s_barrier
	v_add_u32_e32 v83, s12, v237
	ds_read_b64_tr_b16 v[84:85], v83 offset:0
	ds_read_b64_tr_b16 v[86:87], v83 offset:0x800
	ds_read_b64_tr_b16 v[88:89], v83 offset:0x1000
	ds_read_b64_tr_b16 v[90:91], v83 offset:0x1800
	ds_read_b64_tr_b16 v[92:93], v83 offset:0x2000
	ds_read_b64_tr_b16 v[94:95], v83 offset:0x2800
	ds_read_b64_tr_b16 v[96:97], v83 offset:0x3000
	ds_read_b64_tr_b16 v[98:99], v83 offset:0x3800
	s_waitcnt lgkmcnt(0)
	s_nop 0
	v_mfma_f32_32x32x16_bf16 v[2:17], v[78:81], v[84:87], v[2:17]
	ds_read_b64_tr_b16 v[84:85], v83 offset:0x200
	ds_read_b64_tr_b16 v[86:87], v83 offset:0xa00
	v_mfma_f32_32x32x16_bf16 v[2:17], v[74:77], v[88:91], v[2:17]
	ds_read_b64_tr_b16 v[88:89], v83 offset:0x1200
	ds_read_b64_tr_b16 v[90:91], v83 offset:0x1a00
	v_mfma_f32_32x32x16_bf16 v[2:17], v[70:73], v[92:95], v[2:17]
	ds_read_b64_tr_b16 v[92:93], v83 offset:0x2200
	ds_read_b64_tr_b16 v[94:95], v83 offset:0x2a00
	v_mfma_f32_32x32x16_bf16 v[2:17], v[66:69], v[96:99], v[2:17]
	ds_read_b64_tr_b16 v[96:97], v83 offset:0x3200
	ds_read_b64_tr_b16 v[98:99], v83 offset:0x3a00
	s_waitcnt lgkmcnt(0)
	v_mfma_f32_32x32x16_bf16 v[18:33], v[78:81], v[84:87], v[18:33]
	ds_read_b64_tr_b16 v[84:85], v83 offset:0x400
	ds_read_b64_tr_b16 v[86:87], v83 offset:0xc00
	v_mfma_f32_32x32x16_bf16 v[18:33], v[74:77], v[88:91], v[18:33]
	ds_read_b64_tr_b16 v[88:89], v83 offset:0x1400
	ds_read_b64_tr_b16 v[90:91], v83 offset:0x1c00
	v_mfma_f32_32x32x16_bf16 v[18:33], v[70:73], v[92:95], v[18:33]
	ds_read_b64_tr_b16 v[92:93], v83 offset:0x2400
	ds_read_b64_tr_b16 v[94:95], v83 offset:0x2c00
	v_mfma_f32_32x32x16_bf16 v[18:33], v[66:69], v[96:99], v[18:33]
	ds_read_b64_tr_b16 v[96:97], v83 offset:0x3400
	ds_read_b64_tr_b16 v[98:99], v83 offset:0x3c00
	s_waitcnt lgkmcnt(0)
	v_mfma_f32_32x32x16_bf16 v[34:49], v[78:81], v[84:87], v[34:49]
	ds_read_b64_tr_b16 v[84:85], v83 offset:0x600
	ds_read_b64_tr_b16 v[86:87], v83 offset:0xe00
	v_mfma_f32_32x32x16_bf16 v[34:49], v[74:77], v[88:91], v[34:49]
	ds_read_b64_tr_b16 v[88:89], v83 offset:0x1600
	ds_read_b64_tr_b16 v[90:91], v83 offset:0x1e00
	v_mfma_f32_32x32x16_bf16 v[34:49], v[70:73], v[92:95], v[34:49]
	ds_read_b64_tr_b16 v[92:93], v83 offset:0x2600
	ds_read_b64_tr_b16 v[94:95], v83 offset:0x2e00
	v_mfma_f32_32x32x16_bf16 v[34:49], v[66:69], v[96:99], v[34:49]
	ds_read_b64_tr_b16 v[96:97], v83 offset:0x3600
	ds_read_b64_tr_b16 v[98:99], v83 offset:0x3e00
	s_waitcnt lgkmcnt(0)
	v_mfma_f32_32x32x16_bf16 v[50:65], v[78:81], v[84:87], v[50:65]
	s_and_b64 vcc, exec, s[6:7]
	s_barrier
	v_mfma_f32_32x32x16_bf16 v[50:65], v[74:77], v[88:91], v[50:65]
	v_mfma_f32_32x32x16_bf16 v[50:65], v[70:73], v[92:95], v[50:65]
	v_mfma_f32_32x32x16_bf16 v[50:65], v[66:69], v[96:99], v[50:65]
	s_cbranch_vccz .LBB0_304
	s_and_saveexec_b64 s[10:11], s[4:5]
	ds_write_b32 v236, v82
	s_or_b64 exec, exec, s[10:11]
	s_waitcnt lgkmcnt(0)
	v_add_u32_e32 v163, v220, v226
	ds_read_b128 v[130:133], v163
	ds_read_b128 v[134:137], v163 offset:32
	ds_read_b128 v[138:141], v163 offset:64
	ds_read_b128 v[142:145], v163 offset:96
	s_mov_b32 s24, s8
	s_mov_b32 s25, s9
	global_load_ushort v66, v162, s[24:25] offset:3072
	global_load_ushort v67, v162, s[24:25] offset:3136
	global_load_ushort v68, v162, s[24:25] offset:3200
	global_load_ushort v69, v162, s[24:25] offset:3264
	s_add_u32 s24, s24, 0x1400
	s_addc_u32 s25, s25, 0
	global_load_ushort v70, v162, s[24:25] offset:3072
	global_load_ushort v71, v162, s[24:25] offset:3136
	global_load_ushort v72, v162, s[24:25] offset:3200
	global_load_ushort v73, v162, s[24:25] offset:3264
	s_add_u32 s24, s24, 0x1400
	s_addc_u32 s25, s25, 0
	global_load_ushort v74, v162, s[24:25] offset:3072
	global_load_ushort v75, v162, s[24:25] offset:3136
	global_load_ushort v76, v162, s[24:25] offset:3200
	global_load_ushort v77, v162, s[24:25] offset:3264
	s_add_u32 s24, s24, 0x1400
	s_addc_u32 s25, s25, 0
	global_load_ushort v78, v162, s[24:25] offset:3072
	global_load_ushort v79, v162, s[24:25] offset:3136
	global_load_ushort v80, v162, s[24:25] offset:3200
	global_load_ushort v81, v162, s[24:25] offset:3264
	s_add_u32 s24, s24, 0x6400
	s_addc_u32 s25, s25, 0
	global_load_ushort v82, v162, s[24:25] offset:3072
	global_load_ushort v83, v162, s[24:25] offset:3136
	global_load_ushort v84, v162, s[24:25] offset:3200
	global_load_ushort v85, v162, s[24:25] offset:3264
	s_add_u32 s24, s24, 0x1400
	s_addc_u32 s25, s25, 0
	global_load_ushort v86, v162, s[24:25] offset:3072
	global_load_ushort v87, v162, s[24:25] offset:3136
	global_load_ushort v88, v162, s[24:25] offset:3200
	global_load_ushort v89, v162, s[24:25] offset:3264
	s_add_u32 s24, s24, 0x1400
	s_addc_u32 s25, s25, 0
	global_load_ushort v90, v162, s[24:25] offset:3072
	global_load_ushort v91, v162, s[24:25] offset:3136
	global_load_ushort v92, v162, s[24:25] offset:3200
	global_load_ushort v93, v162, s[24:25] offset:3264
	s_add_u32 s24, s24, 0x1400
	s_addc_u32 s25, s25, 0
	global_load_ushort v94, v162, s[24:25] offset:3072
	global_load_ushort v95, v162, s[24:25] offset:3136
	global_load_ushort v96, v162, s[24:25] offset:3200
	global_load_ushort v97, v162, s[24:25] offset:3264
	s_add_u32 s24, s24, 0x6400
	s_addc_u32 s25, s25, 0
	global_load_ushort v98, v162, s[24:25] offset:3072
	global_load_ushort v99, v162, s[24:25] offset:3136
	s_nop 0
	s_nop 0
	s_nop 0
	s_waitcnt lgkmcnt(0)
	v_rcp_f32_e32 v146, v130
	v_rcp_f32_e32 v147, v131
	v_rcp_f32_e32 v148, v132
	v_rcp_f32_e32 v149, v133
	v_rcp_f32_e32 v150, v134
	v_rcp_f32_e32 v151, v135
	v_rcp_f32_e32 v152, v136
	v_rcp_f32_e32 v153, v137
	v_rcp_f32_e32 v154, v138
	v_rcp_f32_e32 v155, v139
	v_rcp_f32_e32 v156, v140
	v_rcp_f32_e32 v157, v141
	v_rcp_f32_e32 v158, v142
	v_rcp_f32_e32 v159, v143
	v_rcp_f32_e32 v160, v144
	v_rcp_f32_e32 v161, v145
	s_waitcnt vmcnt(62)
	v_lshlrev_b32_e32 v100, 16, v100
	v_lshlrev_b32_e32 v101, 16, v101
	v_mul_f32_e32 v164, 0xbfb8aa3b, v100
	v_mul_f32_e32 v165, 0xbfb8aa3b, v101
	v_exp_f32_e32 v164, v164
	v_exp_f32_e32 v165, v165
	v_mul_f32_e32 v166, v42, v154
	v_mul_f32_e32 v167, v58, v154
	v_add_f32_e32 v164, 1.0, v164
	v_add_f32_e32 v165, 1.0, v165
	v_rcp_f32_e32 v164, v164
	v_rcp_f32_e32 v165, v165
	s_nop 0
	v_mul_f32_e32 v100, v164, v100
	v_mul_f32_e32 v101, v165, v101
	v_mul_f32_e32 v100, v166, v100
	v_mul_f32_e32 v101, v167, v101
	v_cvt_pk_bf16_f32 v100, v100, v100
	v_cvt_pk_bf16_f32 v101, v101, v101
	s_waitcnt vmcnt(60)
	v_lshlrev_b32_e32 v102, 16, v102
	v_lshlrev_b32_e32 v103, 16, v103
	v_mul_f32_e32 v164, 0xbfb8aa3b, v102
	v_mul_f32_e32 v165, 0xbfb8aa3b, v103
	v_exp_f32_e32 v164, v164
	v_exp_f32_e32 v165, v165
	v_mul_f32_e32 v166, v11, v155
	v_mul_f32_e32 v167, v27, v155
	v_add_f32_e32 v164, 1.0, v164
	v_add_f32_e32 v165, 1.0, v165
	v_rcp_f32_e32 v164, v164
	v_rcp_f32_e32 v165, v165
	s_nop 0
	v_mul_f32_e32 v102, v164, v102
	v_mul_f32_e32 v103, v165, v103
	v_mul_f32_e32 v102, v166, v102
	v_mul_f32_e32 v103, v167, v103
	v_cvt_pk_bf16_f32 v102, v102, v102
	v_cvt_pk_bf16_f32 v103, v103, v103
	s_waitcnt vmcnt(58)
	v_lshlrev_b32_e32 v104, 16, v104
	v_lshlrev_b32_e32 v105, 16, v105
	v_mul_f32_e32 v164, 0xbfb8aa3b, v104
	v_mul_f32_e32 v165, 0xbfb8aa3b, v105
	v_exp_f32_e32 v164, v164
	v_exp_f32_e32 v165, v165
	v_mul_f32_e32 v166, v43, v155
	v_mul_f32_e32 v167, v59, v155
	v_add_f32_e32 v164, 1.0, v164
	v_add_f32_e32 v165, 1.0, v165
	v_rcp_f32_e32 v164, v164
	v_rcp_f32_e32 v165, v165
	s_nop 0
	v_mul_f32_e32 v104, v164, v104
	v_mul_f32_e32 v105, v165, v105
	v_mul_f32_e32 v104, v166, v104
	v_mul_f32_e32 v105, v167, v105
	v_cvt_pk_bf16_f32 v104, v104, v104
	v_cvt_pk_bf16_f32 v105, v105, v105
	s_waitcnt vmcnt(56)
	v_lshlrev_b32_e32 v106, 16, v106
	v_lshlrev_b32_e32 v107, 16, v107
	v_mul_f32_e32 v164, 0xbfb8aa3b, v106
	v_mul_f32_e32 v165, 0xbfb8aa3b, v107
	v_exp_f32_e32 v164, v164
	v_exp_f32_e32 v165, v165
	v_mul_f32_e32 v166, v12, v156
	v_mul_f32_e32 v167, v28, v156
	v_add_f32_e32 v164, 1.0, v164
	v_add_f32_e32 v165, 1.0, v165
	v_rcp_f32_e32 v164, v164
	v_rcp_f32_e32 v165, v165
	s_nop 0
	v_mul_f32_e32 v106, v164, v106
	v_mul_f32_e32 v107, v165, v107
	v_mul_f32_e32 v106, v166, v106
	v_mul_f32_e32 v107, v167, v107
	v_cvt_pk_bf16_f32 v106, v106, v106
	v_cvt_pk_bf16_f32 v107, v107, v107
	s_waitcnt vmcnt(54)
	v_lshlrev_b32_e32 v108, 16, v108
	v_lshlrev_b32_e32 v109, 16, v109
	v_mul_f32_e32 v164, 0xbfb8aa3b, v108
	v_mul_f32_e32 v165, 0xbfb8aa3b, v109
	v_exp_f32_e32 v164, v164
	v_exp_f32_e32 v165, v165
	v_mul_f32_e32 v166, v44, v156
	v_mul_f32_e32 v167, v60, v156
	v_add_f32_e32 v164, 1.0, v164
	v_add_f32_e32 v165, 1.0, v165
	v_rcp_f32_e32 v164, v164
	v_rcp_f32_e32 v165, v165
	s_nop 0
	v_mul_f32_e32 v108, v164, v108
	v_mul_f32_e32 v109, v165, v109
	v_mul_f32_e32 v108, v166, v108
	v_mul_f32_e32 v109, v167, v109
	v_cvt_pk_bf16_f32 v108, v108, v108
	v_cvt_pk_bf16_f32 v109, v109, v109
	s_waitcnt vmcnt(52)
	v_lshlrev_b32_e32 v110, 16, v110
	v_lshlrev_b32_e32 v111, 16, v111
	v_mul_f32_e32 v164, 0xbfb8aa3b, v110
	v_mul_f32_e32 v165, 0xbfb8aa3b, v111
	v_exp_f32_e32 v164, v164
	v_exp_f32_e32 v165, v165
	v_mul_f32_e32 v166, v13, v157
	v_mul_f32_e32 v167, v29, v157
	v_add_f32_e32 v164, 1.0, v164
	v_add_f32_e32 v165, 1.0, v165
	v_rcp_f32_e32 v164, v164
	v_rcp_f32_e32 v165, v165
	s_nop 0
	v_mul_f32_e32 v110, v164, v110
	v_mul_f32_e32 v111, v165, v111
	v_mul_f32_e32 v110, v166, v110
	v_mul_f32_e32 v111, v167, v111
	v_cvt_pk_bf16_f32 v110, v110, v110
	v_cvt_pk_bf16_f32 v111, v111, v111
	s_waitcnt vmcnt(50)
	v_lshlrev_b32_e32 v112, 16, v112
	v_lshlrev_b32_e32 v113, 16, v113
	v_mul_f32_e32 v164, 0xbfb8aa3b, v112
	v_mul_f32_e32 v165, 0xbfb8aa3b, v113
	v_exp_f32_e32 v164, v164
	v_exp_f32_e32 v165, v165
	v_mul_f32_e32 v166, v45, v157
	v_mul_f32_e32 v167, v61, v157
	v_add_f32_e32 v164, 1.0, v164
	v_add_f32_e32 v165, 1.0, v165
	v_rcp_f32_e32 v164, v164
	v_rcp_f32_e32 v165, v165
	s_nop 0
	v_mul_f32_e32 v112, v164, v112
	v_mul_f32_e32 v113, v165, v113
	v_mul_f32_e32 v112, v166, v112
	v_mul_f32_e32 v113, v167, v113
	v_cvt_pk_bf16_f32 v112, v112, v112
	v_cvt_pk_bf16_f32 v113, v113, v113
	s_waitcnt vmcnt(48)
	v_lshlrev_b32_e32 v114, 16, v114
	v_lshlrev_b32_e32 v115, 16, v115
	v_mul_f32_e32 v164, 0xbfb8aa3b, v114
	v_mul_f32_e32 v165, 0xbfb8aa3b, v115
	v_exp_f32_e32 v164, v164
	v_exp_f32_e32 v165, v165
	v_mul_f32_e32 v166, v14, v158
	v_mul_f32_e32 v167, v30, v158
	v_add_f32_e32 v164, 1.0, v164
	v_add_f32_e32 v165, 1.0, v165
	v_rcp_f32_e32 v164, v164
	v_rcp_f32_e32 v165, v165
	s_nop 0
	v_mul_f32_e32 v114, v164, v114
	v_mul_f32_e32 v115, v165, v115
	v_mul_f32_e32 v114, v166, v114
	v_mul_f32_e32 v115, v167, v115
	v_cvt_pk_bf16_f32 v114, v114, v114
	v_cvt_pk_bf16_f32 v115, v115, v115
	s_waitcnt vmcnt(46)
	v_lshlrev_b32_e32 v116, 16, v116
	v_lshlrev_b32_e32 v117, 16, v117
	v_mul_f32_e32 v164, 0xbfb8aa3b, v116
	v_mul_f32_e32 v165, 0xbfb8aa3b, v117
	v_exp_f32_e32 v164, v164
	v_exp_f32_e32 v165, v165
	v_mul_f32_e32 v166, v46, v158
	v_mul_f32_e32 v167, v62, v158
	v_add_f32_e32 v164, 1.0, v164
	v_add_f32_e32 v165, 1.0, v165
	v_rcp_f32_e32 v164, v164
	v_rcp_f32_e32 v165, v165
	s_nop 0
	v_mul_f32_e32 v116, v164, v116
	v_mul_f32_e32 v117, v165, v117
	v_mul_f32_e32 v116, v166, v116
	v_mul_f32_e32 v117, v167, v117
	v_cvt_pk_bf16_f32 v116, v116, v116
	v_cvt_pk_bf16_f32 v117, v117, v117
	s_waitcnt vmcnt(44)
	v_lshlrev_b32_e32 v118, 16, v118
	v_lshlrev_b32_e32 v119, 16, v119
	v_mul_f32_e32 v164, 0xbfb8aa3b, v118
	v_mul_f32_e32 v165, 0xbfb8aa3b, v119
	v_exp_f32_e32 v164, v164
	v_exp_f32_e32 v165, v165
	v_mul_f32_e32 v166, v15, v159
	v_mul_f32_e32 v167, v31, v159
	v_add_f32_e32 v164, 1.0, v164
	v_add_f32_e32 v165, 1.0, v165
	v_rcp_f32_e32 v164, v164
	v_rcp_f32_e32 v165, v165
	s_nop 0
	v_mul_f32_e32 v118, v164, v118
	v_mul_f32_e32 v119, v165, v119
	v_mul_f32_e32 v118, v166, v118
	v_mul_f32_e32 v119, v167, v119
	v_cvt_pk_bf16_f32 v118, v118, v118
	v_cvt_pk_bf16_f32 v119, v119, v119
	s_waitcnt vmcnt(42)
	v_lshlrev_b32_e32 v120, 16, v120
	v_lshlrev_b32_e32 v121, 16, v121
	v_mul_f32_e32 v164, 0xbfb8aa3b, v120
	v_mul_f32_e32 v165, 0xbfb8aa3b, v121
	v_exp_f32_e32 v164, v164
	v_exp_f32_e32 v165, v165
	v_mul_f32_e32 v166, v47, v159
	v_mul_f32_e32 v167, v63, v159
	v_add_f32_e32 v164, 1.0, v164
	v_add_f32_e32 v165, 1.0, v165
	v_rcp_f32_e32 v164, v164
	v_rcp_f32_e32 v165, v165
	s_nop 0
	v_mul_f32_e32 v120, v164, v120
	v_mul_f32_e32 v121, v165, v121
	v_mul_f32_e32 v120, v166, v120
	v_mul_f32_e32 v121, v167, v121
	v_cvt_pk_bf16_f32 v120, v120, v120
	v_cvt_pk_bf16_f32 v121, v121, v121
	s_waitcnt vmcnt(40)
	v_lshlrev_b32_e32 v122, 16, v122
	v_lshlrev_b32_e32 v123, 16, v123
	v_mul_f32_e32 v164, 0xbfb8aa3b, v122
	v_mul_f32_e32 v165, 0xbfb8aa3b, v123
	v_exp_f32_e32 v164, v164
	v_exp_f32_e32 v165, v165
	v_mul_f32_e32 v166, v16, v160
	v_mul_f32_e32 v167, v32, v160
	v_add_f32_e32 v164, 1.0, v164
	v_add_f32_e32 v165, 1.0, v165
	v_rcp_f32_e32 v164, v164
	v_rcp_f32_e32 v165, v165
	s_nop 0
	v_mul_f32_e32 v122, v164, v122
	v_mul_f32_e32 v123, v165, v123
	v_mul_f32_e32 v122, v166, v122
	v_mul_f32_e32 v123, v167, v123
	v_cvt_pk_bf16_f32 v122, v122, v122
	v_cvt_pk_bf16_f32 v123, v123, v123
	s_waitcnt vmcnt(38)
	v_lshlrev_b32_e32 v124, 16, v124
	v_lshlrev_b32_e32 v125, 16, v125
	v_mul_f32_e32 v164, 0xbfb8aa3b, v124
	v_mul_f32_e32 v165, 0xbfb8aa3b, v125
	v_exp_f32_e32 v164, v164
	v_exp_f32_e32 v165, v165
	v_mul_f32_e32 v166, v48, v160
	v_mul_f32_e32 v167, v64, v160
	v_add_f32_e32 v164, 1.0, v164
	v_add_f32_e32 v165, 1.0, v165
	v_rcp_f32_e32 v164, v164
	v_rcp_f32_e32 v165, v165
	s_nop 0
	v_mul_f32_e32 v124, v164, v124
	v_mul_f32_e32 v125, v165, v125
	v_mul_f32_e32 v124, v166, v124
	v_mul_f32_e32 v125, v167, v125
	v_cvt_pk_bf16_f32 v124, v124, v124
	v_cvt_pk_bf16_f32 v125, v125, v125
	s_waitcnt vmcnt(36)
	v_lshlrev_b32_e32 v126, 16, v126
	v_lshlrev_b32_e32 v127, 16, v127
	v_mul_f32_e32 v164, 0xbfb8aa3b, v126
	v_mul_f32_e32 v165, 0xbfb8aa3b, v127
	v_exp_f32_e32 v164, v164
	v_exp_f32_e32 v165, v165
	v_mul_f32_e32 v166, v17, v161
	v_mul_f32_e32 v167, v33, v161
	v_add_f32_e32 v164, 1.0, v164
	v_add_f32_e32 v165, 1.0, v165
	v_rcp_f32_e32 v164, v164
	v_rcp_f32_e32 v165, v165
	s_nop 0
	v_mul_f32_e32 v126, v164, v126
	v_mul_f32_e32 v127, v165, v127
	v_mul_f32_e32 v126, v166, v126
	v_mul_f32_e32 v127, v167, v127
	v_cvt_pk_bf16_f32 v126, v126, v126
	v_cvt_pk_bf16_f32 v127, v127, v127
	s_waitcnt vmcnt(34)
	v_lshlrev_b32_e32 v128, 16, v128
	v_lshlrev_b32_e32 v129, 16, v129
	v_mul_f32_e32 v164, 0xbfb8aa3b, v128
	v_mul_f32_e32 v165, 0xbfb8aa3b, v129
	v_exp_f32_e32 v164, v164
	v_exp_f32_e32 v165, v165
	v_mul_f32_e32 v166, v49, v161
	v_mul_f32_e32 v167, v65, v161
	v_add_f32_e32 v164, 1.0, v164
	v_add_f32_e32 v165, 1.0, v165
	v_rcp_f32_e32 v164, v164
	v_rcp_f32_e32 v165, v165
	s_nop 0
	v_mul_f32_e32 v128, v164, v128
	v_mul_f32_e32 v129, v165, v129
	v_mul_f32_e32 v128, v166, v128
	v_mul_f32_e32 v129, v167, v129
	v_cvt_pk_bf16_f32 v128, v128, v128
	v_cvt_pk_bf16_f32 v129, v129, v129
	s_waitcnt vmcnt(32)
	v_lshlrev_b32_e32 v66, 16, v66
	v_lshlrev_b32_e32 v67, 16, v67
	v_mul_f32_e32 v164, 0xbfb8aa3b, v66
	v_mul_f32_e32 v165, 0xbfb8aa3b, v67
	v_exp_f32_e32 v164, v164
	v_exp_f32_e32 v165, v165
	v_mul_f32_e32 v166, v2, v146
	v_mul_f32_e32 v167, v18, v146
	v_add_f32_e32 v164, 1.0, v164
	v_add_f32_e32 v165, 1.0, v165
	v_rcp_f32_e32 v164, v164
	v_rcp_f32_e32 v165, v165
	s_nop 0
	v_mul_f32_e32 v66, v164, v66
	v_mul_f32_e32 v67, v165, v67
	v_mul_f32_e32 v66, v166, v66
	v_mul_f32_e32 v67, v167, v67
	v_cvt_pk_bf16_f32 v66, v66, v66
	v_cvt_pk_bf16_f32 v67, v67, v67
	s_waitcnt vmcnt(30)
	v_lshlrev_b32_e32 v68, 16, v68
	v_lshlrev_b32_e32 v69, 16, v69
	v_mul_f32_e32 v164, 0xbfb8aa3b, v68
	v_mul_f32_e32 v165, 0xbfb8aa3b, v69
	v_exp_f32_e32 v164, v164
	v_exp_f32_e32 v165, v165
	v_mul_f32_e32 v166, v34, v146
	v_mul_f32_e32 v167, v50, v146
	v_add_f32_e32 v164, 1.0, v164
	v_add_f32_e32 v165, 1.0, v165
	v_rcp_f32_e32 v164, v164
	v_rcp_f32_e32 v165, v165
	s_nop 0
	v_mul_f32_e32 v68, v164, v68
	v_mul_f32_e32 v69, v165, v69
	v_mul_f32_e32 v68, v166, v68
	v_mul_f32_e32 v69, v167, v69
	v_cvt_pk_bf16_f32 v68, v68, v68
	v_cvt_pk_bf16_f32 v69, v69, v69
	s_waitcnt vmcnt(28)
	v_lshlrev_b32_e32 v70, 16, v70
	v_lshlrev_b32_e32 v71, 16, v71
	v_mul_f32_e32 v164, 0xbfb8aa3b, v70
	v_mul_f32_e32 v165, 0xbfb8aa3b, v71
	v_exp_f32_e32 v164, v164
	v_exp_f32_e32 v165, v165
	v_mul_f32_e32 v166, v3, v147
	v_mul_f32_e32 v167, v19, v147
	v_add_f32_e32 v164, 1.0, v164
	v_add_f32_e32 v165, 1.0, v165
	v_rcp_f32_e32 v164, v164
	v_rcp_f32_e32 v165, v165
	s_nop 0
	v_mul_f32_e32 v70, v164, v70
	v_mul_f32_e32 v71, v165, v71
	v_mul_f32_e32 v70, v166, v70
	v_mul_f32_e32 v71, v167, v71
	v_cvt_pk_bf16_f32 v70, v70, v70
	v_cvt_pk_bf16_f32 v71, v71, v71
	s_waitcnt vmcnt(26)
	v_lshlrev_b32_e32 v72, 16, v72
	v_lshlrev_b32_e32 v73, 16, v73
	v_mul_f32_e32 v164, 0xbfb8aa3b, v72
	v_mul_f32_e32 v165, 0xbfb8aa3b, v73
	v_exp_f32_e32 v164, v164
	v_exp_f32_e32 v165, v165
	v_mul_f32_e32 v166, v35, v147
	v_mul_f32_e32 v167, v51, v147
	v_add_f32_e32 v164, 1.0, v164
	v_add_f32_e32 v165, 1.0, v165
	v_rcp_f32_e32 v164, v164
	v_rcp_f32_e32 v165, v165
	s_nop 0
	v_mul_f32_e32 v72, v164, v72
	v_mul_f32_e32 v73, v165, v73
	v_mul_f32_e32 v72, v166, v72
	v_mul_f32_e32 v73, v167, v73
	v_cvt_pk_bf16_f32 v72, v72, v72
	v_cvt_pk_bf16_f32 v73, v73, v73
	s_waitcnt vmcnt(24)
	v_lshlrev_b32_e32 v74, 16, v74
	v_lshlrev_b32_e32 v75, 16, v75
	v_mul_f32_e32 v164, 0xbfb8aa3b, v74
	v_mul_f32_e32 v165, 0xbfb8aa3b, v75
	v_exp_f32_e32 v164, v164
	v_exp_f32_e32 v165, v165
	v_mul_f32_e32 v166, v4, v148
	v_mul_f32_e32 v167, v20, v148
	v_add_f32_e32 v164, 1.0, v164
	v_add_f32_e32 v165, 1.0, v165
	v_rcp_f32_e32 v164, v164
	v_rcp_f32_e32 v165, v165
	s_nop 0
	v_mul_f32_e32 v74, v164, v74
	v_mul_f32_e32 v75, v165, v75
	v_mul_f32_e32 v74, v166, v74
	v_mul_f32_e32 v75, v167, v75
	v_cvt_pk_bf16_f32 v74, v74, v74
	v_cvt_pk_bf16_f32 v75, v75, v75
	s_waitcnt vmcnt(22)
	v_lshlrev_b32_e32 v76, 16, v76
	v_lshlrev_b32_e32 v77, 16, v77
	v_mul_f32_e32 v164, 0xbfb8aa3b, v76
	v_mul_f32_e32 v165, 0xbfb8aa3b, v77
	v_exp_f32_e32 v164, v164
	v_exp_f32_e32 v165, v165
	v_mul_f32_e32 v166, v36, v148
	v_mul_f32_e32 v167, v52, v148
	v_add_f32_e32 v164, 1.0, v164
	v_add_f32_e32 v165, 1.0, v165
	v_rcp_f32_e32 v164, v164
	v_rcp_f32_e32 v165, v165
	s_nop 0
	v_mul_f32_e32 v76, v164, v76
	v_mul_f32_e32 v77, v165, v77
	v_mul_f32_e32 v76, v166, v76
	v_mul_f32_e32 v77, v167, v77
	v_cvt_pk_bf16_f32 v76, v76, v76
	v_cvt_pk_bf16_f32 v77, v77, v77
	s_waitcnt vmcnt(20)
	v_lshlrev_b32_e32 v78, 16, v78
	v_lshlrev_b32_e32 v79, 16, v79
	v_mul_f32_e32 v164, 0xbfb8aa3b, v78
	v_mul_f32_e32 v165, 0xbfb8aa3b, v79
	v_exp_f32_e32 v164, v164
	v_exp_f32_e32 v165, v165
	v_mul_f32_e32 v166, v5, v149
	v_mul_f32_e32 v167, v21, v149
	v_add_f32_e32 v164, 1.0, v164
	v_add_f32_e32 v165, 1.0, v165
	v_rcp_f32_e32 v164, v164
	v_rcp_f32_e32 v165, v165
	s_nop 0
	v_mul_f32_e32 v78, v164, v78
	v_mul_f32_e32 v79, v165, v79
	v_mul_f32_e32 v78, v166, v78
	v_mul_f32_e32 v79, v167, v79
	v_cvt_pk_bf16_f32 v78, v78, v78
	v_cvt_pk_bf16_f32 v79, v79, v79
	s_waitcnt vmcnt(18)
	v_lshlrev_b32_e32 v80, 16, v80
	v_lshlrev_b32_e32 v81, 16, v81
	v_mul_f32_e32 v164, 0xbfb8aa3b, v80
	v_mul_f32_e32 v165, 0xbfb8aa3b, v81
	v_exp_f32_e32 v164, v164
	v_exp_f32_e32 v165, v165
	v_mul_f32_e32 v166, v37, v149
	v_mul_f32_e32 v167, v53, v149
	v_add_f32_e32 v164, 1.0, v164
	v_add_f32_e32 v165, 1.0, v165
	v_rcp_f32_e32 v164, v164
	v_rcp_f32_e32 v165, v165
	s_nop 0
	v_mul_f32_e32 v80, v164, v80
	v_mul_f32_e32 v81, v165, v81
	v_mul_f32_e32 v80, v166, v80
	v_mul_f32_e32 v81, v167, v81
	v_cvt_pk_bf16_f32 v80, v80, v80
	v_cvt_pk_bf16_f32 v81, v81, v81
	s_waitcnt vmcnt(16)
	v_lshlrev_b32_e32 v82, 16, v82
	v_lshlrev_b32_e32 v83, 16, v83
	v_mul_f32_e32 v164, 0xbfb8aa3b, v82
	v_mul_f32_e32 v165, 0xbfb8aa3b, v83
	v_exp_f32_e32 v164, v164
	v_exp_f32_e32 v165, v165
	v_mul_f32_e32 v166, v6, v150
	v_mul_f32_e32 v167, v22, v150
	v_add_f32_e32 v164, 1.0, v164
	v_add_f32_e32 v165, 1.0, v165
	v_rcp_f32_e32 v164, v164
	v_rcp_f32_e32 v165, v165
	s_nop 0
	v_mul_f32_e32 v82, v164, v82
	v_mul_f32_e32 v83, v165, v83
	v_mul_f32_e32 v82, v166, v82
	v_mul_f32_e32 v83, v167, v83
	v_cvt_pk_bf16_f32 v82, v82, v82
	v_cvt_pk_bf16_f32 v83, v83, v83
	s_waitcnt vmcnt(14)
	v_lshlrev_b32_e32 v84, 16, v84
	v_lshlrev_b32_e32 v85, 16, v85
	v_mul_f32_e32 v164, 0xbfb8aa3b, v84
	v_mul_f32_e32 v165, 0xbfb8aa3b, v85
	v_exp_f32_e32 v164, v164
	v_exp_f32_e32 v165, v165
	v_mul_f32_e32 v166, v38, v150
	v_mul_f32_e32 v167, v54, v150
	v_add_f32_e32 v164, 1.0, v164
	v_add_f32_e32 v165, 1.0, v165
	v_rcp_f32_e32 v164, v164
	v_rcp_f32_e32 v165, v165
	s_nop 0
	v_mul_f32_e32 v84, v164, v84
	v_mul_f32_e32 v85, v165, v85
	v_mul_f32_e32 v84, v166, v84
	v_mul_f32_e32 v85, v167, v85
	v_cvt_pk_bf16_f32 v84, v84, v84
	v_cvt_pk_bf16_f32 v85, v85, v85
	s_waitcnt vmcnt(12)
	v_lshlrev_b32_e32 v86, 16, v86
	v_lshlrev_b32_e32 v87, 16, v87
	v_mul_f32_e32 v164, 0xbfb8aa3b, v86
	v_mul_f32_e32 v165, 0xbfb8aa3b, v87
	v_exp_f32_e32 v164, v164
	v_exp_f32_e32 v165, v165
	v_mul_f32_e32 v166, v7, v151
	v_mul_f32_e32 v167, v23, v151
	v_add_f32_e32 v164, 1.0, v164
	v_add_f32_e32 v165, 1.0, v165
	v_rcp_f32_e32 v164, v164
	v_rcp_f32_e32 v165, v165
	s_nop 0
	v_mul_f32_e32 v86, v164, v86
	v_mul_f32_e32 v87, v165, v87
	v_mul_f32_e32 v86, v166, v86
	v_mul_f32_e32 v87, v167, v87
	v_cvt_pk_bf16_f32 v86, v86, v86
	v_cvt_pk_bf16_f32 v87, v87, v87
	s_waitcnt vmcnt(10)
	v_lshlrev_b32_e32 v88, 16, v88
	v_lshlrev_b32_e32 v89, 16, v89
	v_mul_f32_e32 v164, 0xbfb8aa3b, v88
	v_mul_f32_e32 v165, 0xbfb8aa3b, v89
	v_exp_f32_e32 v164, v164
	v_exp_f32_e32 v165, v165
	v_mul_f32_e32 v166, v39, v151
	v_mul_f32_e32 v167, v55, v151
	v_add_f32_e32 v164, 1.0, v164
	v_add_f32_e32 v165, 1.0, v165
	v_rcp_f32_e32 v164, v164
	v_rcp_f32_e32 v165, v165
	s_nop 0
	v_mul_f32_e32 v88, v164, v88
	v_mul_f32_e32 v89, v165, v89
	v_mul_f32_e32 v88, v166, v88
	v_mul_f32_e32 v89, v167, v89
	v_cvt_pk_bf16_f32 v88, v88, v88
	v_cvt_pk_bf16_f32 v89, v89, v89
	s_waitcnt vmcnt(8)
	v_lshlrev_b32_e32 v90, 16, v90
	v_lshlrev_b32_e32 v91, 16, v91
	v_mul_f32_e32 v164, 0xbfb8aa3b, v90
	v_mul_f32_e32 v165, 0xbfb8aa3b, v91
	v_exp_f32_e32 v164, v164
	v_exp_f32_e32 v165, v165
	v_mul_f32_e32 v166, v8, v152
	v_mul_f32_e32 v167, v24, v152
	v_add_f32_e32 v164, 1.0, v164
	v_add_f32_e32 v165, 1.0, v165
	v_rcp_f32_e32 v164, v164
	v_rcp_f32_e32 v165, v165
	s_nop 0
	v_mul_f32_e32 v90, v164, v90
	v_mul_f32_e32 v91, v165, v91
	v_mul_f32_e32 v90, v166, v90
	v_mul_f32_e32 v91, v167, v91
	v_cvt_pk_bf16_f32 v90, v90, v90
	v_cvt_pk_bf16_f32 v91, v91, v91
	s_waitcnt vmcnt(6)
	v_lshlrev_b32_e32 v92, 16, v92
	v_lshlrev_b32_e32 v93, 16, v93
	v_mul_f32_e32 v164, 0xbfb8aa3b, v92
	v_mul_f32_e32 v165, 0xbfb8aa3b, v93
	v_exp_f32_e32 v164, v164
	v_exp_f32_e32 v165, v165
	v_mul_f32_e32 v166, v40, v152
	v_mul_f32_e32 v167, v56, v152
	v_add_f32_e32 v164, 1.0, v164
	v_add_f32_e32 v165, 1.0, v165
	v_rcp_f32_e32 v164, v164
	v_rcp_f32_e32 v165, v165
	s_nop 0
	v_mul_f32_e32 v92, v164, v92
	v_mul_f32_e32 v93, v165, v93
	v_mul_f32_e32 v92, v166, v92
	v_mul_f32_e32 v93, v167, v93
	v_cvt_pk_bf16_f32 v92, v92, v92
	v_cvt_pk_bf16_f32 v93, v93, v93
	s_waitcnt vmcnt(4)
	v_lshlrev_b32_e32 v94, 16, v94
	v_lshlrev_b32_e32 v95, 16, v95
	v_mul_f32_e32 v164, 0xbfb8aa3b, v94
	v_mul_f32_e32 v165, 0xbfb8aa3b, v95
	v_exp_f32_e32 v164, v164
	v_exp_f32_e32 v165, v165
	v_mul_f32_e32 v166, v9, v153
	v_mul_f32_e32 v167, v25, v153
	v_add_f32_e32 v164, 1.0, v164
	v_add_f32_e32 v165, 1.0, v165
	v_rcp_f32_e32 v164, v164
	v_rcp_f32_e32 v165, v165
	s_nop 0
	v_mul_f32_e32 v94, v164, v94
	v_mul_f32_e32 v95, v165, v95
	v_mul_f32_e32 v94, v166, v94
	v_mul_f32_e32 v95, v167, v95
	v_cvt_pk_bf16_f32 v94, v94, v94
	v_cvt_pk_bf16_f32 v95, v95, v95
	s_waitcnt vmcnt(2)
	v_lshlrev_b32_e32 v96, 16, v96
	v_lshlrev_b32_e32 v97, 16, v97
	v_mul_f32_e32 v164, 0xbfb8aa3b, v96
	v_mul_f32_e32 v165, 0xbfb8aa3b, v97
	v_exp_f32_e32 v164, v164
	v_exp_f32_e32 v165, v165
	v_mul_f32_e32 v166, v41, v153
	v_mul_f32_e32 v167, v57, v153
	v_add_f32_e32 v164, 1.0, v164
	v_add_f32_e32 v165, 1.0, v165
	v_rcp_f32_e32 v164, v164
	v_rcp_f32_e32 v165, v165
	s_nop 0
	v_mul_f32_e32 v96, v164, v96
	v_mul_f32_e32 v97, v165, v97
	v_mul_f32_e32 v96, v166, v96
	v_mul_f32_e32 v97, v167, v97
	v_cvt_pk_bf16_f32 v96, v96, v96
	v_cvt_pk_bf16_f32 v97, v97, v97
	s_waitcnt vmcnt(0)
	v_lshlrev_b32_e32 v98, 16, v98
	v_lshlrev_b32_e32 v99, 16, v99
	v_mul_f32_e32 v164, 0xbfb8aa3b, v98
	v_mul_f32_e32 v165, 0xbfb8aa3b, v99
	v_exp_f32_e32 v164, v164
	v_exp_f32_e32 v165, v165
	v_mul_f32_e32 v166, v10, v154
	v_mul_f32_e32 v167, v26, v154
	v_add_f32_e32 v164, 1.0, v164
	v_add_f32_e32 v165, 1.0, v165
	v_rcp_f32_e32 v164, v164
	v_rcp_f32_e32 v165, v165
	s_nop 0
	v_mul_f32_e32 v98, v164, v98
	v_mul_f32_e32 v99, v165, v99
	v_mul_f32_e32 v98, v166, v98
	v_mul_f32_e32 v99, v167, v99
	v_cvt_pk_bf16_f32 v98, v98, v98
	v_cvt_pk_bf16_f32 v99, v99, v99
	s_mov_b32 s24, s8
	s_mov_b32 s25, s9
	global_store_short v162, v66, s[24:25] offset:3072
	global_store_short v162, v67, s[24:25] offset:3136
	global_store_short v162, v68, s[24:25] offset:3200
	global_store_short v162, v69, s[24:25] offset:3264
	s_add_u32 s24, s24, 0x1400
	s_addc_u32 s25, s25, 0
	global_store_short v162, v70, s[24:25] offset:3072
	global_store_short v162, v71, s[24:25] offset:3136
	global_store_short v162, v72, s[24:25] offset:3200
	global_store_short v162, v73, s[24:25] offset:3264
	s_add_u32 s24, s24, 0x1400
	s_addc_u32 s25, s25, 0
	global_store_short v162, v74, s[24:25] offset:3072
	global_store_short v162, v75, s[24:25] offset:3136
	global_store_short v162, v76, s[24:25] offset:3200
	global_store_short v162, v77, s[24:25] offset:3264
	s_add_u32 s24, s24, 0x1400
	s_addc_u32 s25, s25, 0
	global_store_short v162, v78, s[24:25] offset:3072
	global_store_short v162, v79, s[24:25] offset:3136
	global_store_short v162, v80, s[24:25] offset:3200
	global_store_short v162, v81, s[24:25] offset:3264
	s_add_u32 s24, s24, 0x6400
	s_addc_u32 s25, s25, 0
	global_store_short v162, v82, s[24:25] offset:3072
	global_store_short v162, v83, s[24:25] offset:3136
	global_store_short v162, v84, s[24:25] offset:3200
	global_store_short v162, v85, s[24:25] offset:3264
	s_add_u32 s24, s24, 0x1400
	s_addc_u32 s25, s25, 0
	global_store_short v162, v86, s[24:25] offset:3072
	global_store_short v162, v87, s[24:25] offset:3136
	global_store_short v162, v88, s[24:25] offset:3200
	global_store_short v162, v89, s[24:25] offset:3264
	s_add_u32 s24, s24, 0x1400
	s_addc_u32 s25, s25, 0
	global_store_short v162, v90, s[24:25] offset:3072
	global_store_short v162, v91, s[24:25] offset:3136
	global_store_short v162, v92, s[24:25] offset:3200
	global_store_short v162, v93, s[24:25] offset:3264
	s_add_u32 s24, s24, 0x1400
	s_addc_u32 s25, s25, 0
	global_store_short v162, v94, s[24:25] offset:3072
	global_store_short v162, v95, s[24:25] offset:3136
	global_store_short v162, v96, s[24:25] offset:3200
	global_store_short v162, v97, s[24:25] offset:3264
	s_add_u32 s24, s24, 0x6400
	s_addc_u32 s25, s25, 0
	global_store_short v162, v98, s[24:25] offset:3072
	global_store_short v162, v99, s[24:25] offset:3136
	global_store_short v162, v100, s[24:25] offset:3200
	global_store_short v162, v101, s[24:25] offset:3264
	s_add_u32 s24, s24, 0x1400
	s_addc_u32 s25, s25, 0
	global_store_short v162, v102, s[24:25] offset:3072
	global_store_short v162, v103, s[24:25] offset:3136
	global_store_short v162, v104, s[24:25] offset:3200
	global_store_short v162, v105, s[24:25] offset:3264
	s_add_u32 s24, s24, 0x1400
	s_addc_u32 s25, s25, 0
	global_store_short v162, v106, s[24:25] offset:3072
	global_store_short v162, v107, s[24:25] offset:3136
	global_store_short v162, v108, s[24:25] offset:3200
	global_store_short v162, v109, s[24:25] offset:3264
	s_add_u32 s24, s24, 0x1400
	s_addc_u32 s25, s25, 0
	global_store_short v162, v110, s[24:25] offset:3072
	global_store_short v162, v111, s[24:25] offset:3136
	global_store_short v162, v112, s[24:25] offset:3200
	global_store_short v162, v113, s[24:25] offset:3264
	s_add_u32 s24, s24, 0x6400
	s_addc_u32 s25, s25, 0
	global_store_short v162, v114, s[24:25] offset:3072
	global_store_short v162, v115, s[24:25] offset:3136
	global_store_short v162, v116, s[24:25] offset:3200
	global_store_short v162, v117, s[24:25] offset:3264
	s_add_u32 s24, s24, 0x1400
	s_addc_u32 s25, s25, 0
	global_store_short v162, v118, s[24:25] offset:3072
	global_store_short v162, v119, s[24:25] offset:3136
	global_store_short v162, v120, s[24:25] offset:3200
	global_store_short v162, v121, s[24:25] offset:3264
	s_add_u32 s24, s24, 0x1400
	s_addc_u32 s25, s25, 0
	global_store_short v162, v122, s[24:25] offset:3072
	global_store_short v162, v123, s[24:25] offset:3136
	global_store_short v162, v124, s[24:25] offset:3200
	global_store_short v162, v125, s[24:25] offset:3264
	s_add_u32 s24, s24, 0x1400
	s_addc_u32 s25, s25, 0
	global_store_short v162, v126, s[24:25] offset:3072
	global_store_short v162, v127, s[24:25] offset:3136
	global_store_short v162, v128, s[24:25] offset:3200
	global_store_short v162, v129, s[24:25] offset:3264
	s_branch .LBB0_276
	s_nop 0
	s_nop 0
	s_nop 0
	s_nop 0
	s_nop 0
	s_nop 0
	s_nop 0
	s_nop 0
	s_nop 0
	s_nop 0
	s_nop 0
	s_nop 0
	s_nop 0
	s_nop 0
	s_nop 0
	s_nop 0
	s_nop 0
	s_nop 0
	s_nop 0
	s_nop 0
	s_nop 0
	s_nop 0
	s_nop 0
	s_nop 0
	s_nop 0
	s_nop 0
	s_nop 0
	s_nop 0
	s_nop 0
	s_nop 0
	s_nop 0
	s_nop 0
	s_nop 0
	s_nop 0
	s_nop 0
	s_nop 0
	s_nop 0
	s_nop 0
	s_nop 0
	s_nop 0
	s_nop 0
	s_nop 0
	s_nop 0
	s_nop 0
	s_nop 0
	s_nop 0
	s_nop 0
	s_nop 0
